# on top of v196: nt hint on the PAPR-tail stores of the transposed f2d weights, which are first read two GEMM phases later
# speedup vs baseline: 1.0053x; 1.0053x over previous
.LBB0_1482:
	s_lshl_b32 s25, s22, 1
	s_lshl_b32 s26, s23, 1
	v_or_b32_e32 v11, s25, v1
	v_or_b32_e32 v17, s26, v4
	s_add_i32 s27, s25, 4
	s_add_i32 s28, s26, 4
	s_add_i32 s29, s25, 8
	s_add_i32 s30, s26, 8
	s_add_i32 s31, s25, 12
	s_add_i32 s52, s26, 12
	s_add_i32 s53, s25, 16
	s_add_i32 s57, s26, 16
	s_add_i32 s58, s25, 20
	s_add_i32 s59, s26, 20
	s_add_i32 s60, s25, 24
	s_add_i32 s61, s26, 24
	s_add_i32 s25, s25, 28
	s_add_i32 s26, s26, 28
	v_add_u32_e32 v25, v11, v3
	v_add_u32_e32 v28, v17, v16
	v_or_b32_e32 v87, s27, v1
	v_or_b32_e32 v89, s28, v4
	v_or_b32_e32 v90, s29, v1
	v_or_b32_e32 v91, s30, v4
	v_or_b32_e32 v92, s31, v1
	v_or_b32_e32 v93, s52, v4
	v_or_b32_e32 v94, s53, v1
	v_or_b32_e32 v95, s57, v4
	v_or_b32_e32 v96, s58, v1
	v_or_b32_e32 v97, s59, v4
	v_or_b32_e32 v98, s60, v1
	v_or_b32_e32 v99, s61, v4
	v_or_b32_e32 v100, s25, v1
	v_or_b32_e32 v101, s26, v4
	v_ashrrev_i32_e32 v33, 31, v28
	v_ashrrev_i32_e32 v31, 31, v25
	v_mad_u64_u32 v[26:27], s[26:27], v2, v25, 0
	v_mad_u64_u32 v[28:29], s[26:27], v0, v28, 0
	v_add_u32_e32 v25, v87, v3
	v_add_u32_e32 v36, v89, v16
	v_add_u32_e32 v38, v90, v3
	v_add_u32_e32 v40, v91, v16
	v_add_u32_e32 v42, v92, v3
	v_add_u32_e32 v44, v93, v16
	v_add_u32_e32 v46, v94, v3
	v_add_u32_e32 v48, v95, v16
	v_add_u32_e32 v50, v96, v3
	v_add_u32_e32 v52, v97, v16
	v_add_u32_e32 v54, v98, v3
	v_add_u32_e32 v56, v99, v16
	v_add_u32_e32 v58, v100, v3
	v_add_u32_e32 v60, v101, v16
	v_mov_b32_e32 v30, v27
	v_mov_b32_e32 v32, v29
	v_ashrrev_i32_e32 v63, 31, v36
	v_ashrrev_i32_e32 v65, 31, v25
	v_mad_u64_u32 v[34:35], s[26:27], v2, v25, 0
	v_mad_u64_u32 v[36:37], s[26:27], v0, v36, 0
	v_ashrrev_i32_e32 v25, 31, v40
	v_ashrrev_i32_e32 v67, 31, v38
	v_mad_u64_u32 v[38:39], s[26:27], v2, v38, 0
	v_mad_u64_u32 v[40:41], s[26:27], v0, v40, 0
	v_ashrrev_i32_e32 v69, 31, v44
	v_ashrrev_i32_e32 v71, 31, v42
	v_mad_u64_u32 v[42:43], s[26:27], v2, v42, 0
	v_mad_u64_u32 v[44:45], s[26:27], v0, v44, 0
	v_ashrrev_i32_e32 v73, 31, v48
	v_ashrrev_i32_e32 v75, 31, v46
	v_mad_u64_u32 v[46:47], s[26:27], v2, v46, 0
	v_mad_u64_u32 v[48:49], s[26:27], v0, v48, 0
	v_ashrrev_i32_e32 v77, 31, v52
	v_ashrrev_i32_e32 v79, 31, v50
	v_mad_u64_u32 v[50:51], s[26:27], v2, v50, 0
	v_mad_u64_u32 v[52:53], s[26:27], v0, v52, 0
	v_ashrrev_i32_e32 v81, 31, v56
	v_ashrrev_i32_e32 v83, 31, v54
	v_mad_u64_u32 v[54:55], s[26:27], v2, v54, 0
	v_mad_u64_u32 v[56:57], s[26:27], v0, v56, 0
	v_ashrrev_i32_e32 v85, 31, v60
	v_ashrrev_i32_e32 v102, 31, v58
	v_mad_u64_u32 v[58:59], s[26:27], v2, v58, 0
	v_mad_u64_u32 v[60:61], s[26:27], v0, v60, 0
	v_mad_u64_u32 v[30:31], s[26:27], v2, v31, v[30:31]
	v_mad_u64_u32 v[32:33], s[26:27], v0, v33, v[32:33]
	v_mov_b32_e32 v62, v35
	v_mov_b32_e32 v64, v37
	v_mov_b32_e32 v66, v39
	v_mov_b32_e32 v68, v41
	v_mov_b32_e32 v70, v43
	v_mov_b32_e32 v72, v45
	v_mov_b32_e32 v74, v47
	v_mov_b32_e32 v76, v49
	v_mov_b32_e32 v78, v51
	v_mov_b32_e32 v80, v53
	v_mov_b32_e32 v82, v55
	v_mov_b32_e32 v84, v57
	v_mov_b32_e32 v86, v59
	v_mov_b32_e32 v88, v61
	v_mov_b32_e32 v27, v30
	v_mov_b32_e32 v29, v32
	v_mad_u64_u32 v[30:31], s[26:27], v2, v65, v[62:63]
	v_mad_u64_u32 v[32:33], s[26:27], v0, v63, v[64:65]
	v_mad_u64_u32 v[62:63], s[26:27], v2, v67, v[66:67]
	v_mad_u64_u32 v[64:65], s[26:27], v0, v25, v[68:69]
	v_mad_u64_u32 v[66:67], s[26:27], v2, v71, v[70:71]
	v_mad_u64_u32 v[68:69], s[26:27], v0, v69, v[72:73]
	v_mad_u64_u32 v[70:71], s[26:27], v2, v75, v[74:75]
	v_mad_u64_u32 v[72:73], s[26:27], v0, v73, v[76:77]
	v_mad_u64_u32 v[74:75], s[26:27], v2, v79, v[78:79]
	v_mad_u64_u32 v[76:77], s[26:27], v0, v77, v[80:81]
	v_mad_u64_u32 v[78:79], s[26:27], v2, v83, v[82:83]
	v_mad_u64_u32 v[80:81], s[26:27], v0, v81, v[84:85]
	v_mad_u64_u32 v[82:83], s[26:27], v2, v102, v[86:87]
	v_mad_u64_u32 v[84:85], s[26:27], v0, v85, v[88:89]
	v_lshl_add_u64 v[28:29], v[28:29], 2, v[18:19]
	v_mov_b32_e32 v35, v30
	v_mov_b32_e32 v37, v32
	v_mov_b32_e32 v39, v62
	v_mov_b32_e32 v41, v64
	v_mov_b32_e32 v43, v66
	v_mov_b32_e32 v45, v68
	v_mov_b32_e32 v47, v70
	v_mov_b32_e32 v49, v72
	v_mov_b32_e32 v51, v74
	v_mov_b32_e32 v53, v76
	v_mov_b32_e32 v55, v78
	v_mov_b32_e32 v57, v80
	v_mov_b32_e32 v59, v82
	v_mov_b32_e32 v61, v84
	v_lshl_add_u64 v[26:27], v[26:27], 2, v[18:19]
	v_lshl_add_u64 v[30:31], v[36:37], 2, v[18:19]
	v_lshl_add_u64 v[32:33], v[34:35], 2, v[18:19]
	v_lshl_add_u64 v[34:35], v[40:41], 2, v[18:19]
	v_lshl_add_u64 v[36:37], v[38:39], 2, v[18:19]
	v_lshl_add_u64 v[38:39], v[44:45], 2, v[18:19]
	v_lshl_add_u64 v[40:41], v[42:43], 2, v[18:19]
	v_lshl_add_u64 v[42:43], v[48:49], 2, v[18:19]
	v_lshl_add_u64 v[44:45], v[46:47], 2, v[18:19]
	v_lshl_add_u64 v[46:47], v[52:53], 2, v[18:19]
	v_lshl_add_u64 v[48:49], v[50:51], 2, v[18:19]
	v_lshl_add_u64 v[50:51], v[56:57], 2, v[18:19]
	v_lshl_add_u64 v[52:53], v[54:55], 2, v[18:19]
	v_lshl_add_u64 v[54:55], v[60:61], 2, v[18:19]
	v_lshl_add_u64 v[56:57], v[58:59], 2, v[18:19]
	global_load_dword v25, v[28:29], off nt
	global_load_dword v58, v[26:27], off nt
	global_load_dword v59, v[30:31], off nt
	global_load_dword v60, v[32:33], off nt
	global_load_dword v61, v[34:35], off nt
	global_load_dword v62, v[36:37], off nt
	global_load_dword v63, v[38:39], off nt
	global_load_dword v64, v[40:41], off nt
	global_load_dword v65, v[42:43], off nt
	global_load_dword v66, v[44:45], off nt
	global_load_dword v67, v[46:47], off nt
	global_load_dword v68, v[48:49], off nt
	global_load_dword v69, v[50:51], off nt
	global_load_dword v70, v[52:53], off nt
	global_load_dword v71, v[54:55], off nt
	global_load_dword v72, v[56:57], off nt
	s_add_i32 s23, s23, 16
	s_add_i32 s22, s22, 16
	s_add_i32 s24, s24, -16
	v_mad_u64_u32 v[26:27], s[26:27], v17, s35, v[8:9]
	s_cmp_lg_u32 s24, 0
	v_mad_u64_u32 v[28:29], s[26:27], v11, s35, v[8:9]
	v_mad_u64_u32 v[30:31], s[26:27], v89, s35, v[8:9]
	v_mad_u64_u32 v[32:33], s[26:27], v87, s35, v[8:9]
	v_mad_u64_u32 v[34:35], s[26:27], v91, s35, v[8:9]
	v_mad_u64_u32 v[36:37], s[26:27], v90, s35, v[8:9]
	v_mad_u64_u32 v[38:39], s[26:27], v93, s35, v[8:9]
	v_mad_u64_u32 v[40:41], s[26:27], v92, s35, v[8:9]
	v_mad_u64_u32 v[42:43], s[26:27], v95, s35, v[8:9]
	v_mad_u64_u32 v[44:45], s[26:27], v94, s35, v[8:9]
	v_mad_u64_u32 v[46:47], s[26:27], v97, s35, v[8:9]
	v_mad_u64_u32 v[48:49], s[26:27], v96, s35, v[8:9]
	v_mad_u64_u32 v[50:51], s[26:27], v99, s35, v[8:9]
	v_mad_u64_u32 v[52:53], s[26:27], v98, s35, v[8:9]
	v_mad_u64_u32 v[54:55], s[26:27], v101, s35, v[8:9]
	v_mad_u64_u32 v[56:57], s[26:27], v100, s35, v[8:9]
	s_waitcnt vmcnt(15)
	ds_write_b32 v26, v25
	s_waitcnt vmcnt(14)
	ds_write_b32 v28, v58
	s_waitcnt vmcnt(13)
	ds_write_b32 v30, v59
	s_waitcnt vmcnt(12)
	ds_write_b32 v32, v60
	s_waitcnt vmcnt(11)
	ds_write_b32 v34, v61
	s_waitcnt vmcnt(10)
	ds_write_b32 v36, v62
	s_waitcnt vmcnt(9)
	ds_write_b32 v38, v63
	s_waitcnt vmcnt(8)
	ds_write_b32 v40, v64
	s_waitcnt vmcnt(7)
	ds_write_b32 v42, v65
	s_waitcnt vmcnt(6)
	ds_write_b32 v44, v66
	s_waitcnt vmcnt(5)
	ds_write_b32 v46, v67
	s_waitcnt vmcnt(4)
	ds_write_b32 v48, v68
	s_waitcnt vmcnt(3)
	ds_write_b32 v50, v69
	s_waitcnt vmcnt(2)
	ds_write_b32 v52, v70
	s_waitcnt vmcnt(1)
	ds_write_b32 v54, v71
	s_waitcnt vmcnt(0)
	ds_write_b32 v56, v72
	s_cbranch_scc1 .LBB0_1482
	s_waitcnt lgkmcnt(0)
	v_ashrrev_i32_e32 v17, 31, v16
	ds_read2_b32 v[18:19], v20 offset0:33 offset1:41
	ds_read2_b32 v[26:27], v20 offset1:8
	ds_read2_b32 v[28:29], v20 offset0:66 offset1:74
	ds_read2_b32 v[30:31], v20 offset0:99 offset1:107
	ds_read2_b32 v[32:33], v20 offset0:132 offset1:140
	ds_read2_b32 v[34:35], v20 offset0:165 offset1:173
	ds_read2_b32 v[36:37], v20 offset0:198 offset1:206
	ds_read2_b32 v[38:39], v20 offset0:231 offset1:239
	v_lshl_add_u64 v[2:3], v[16:17], 1, v[14:15]
	v_mov_b32_e32 v11, v7
	v_add_u32_e32 v0, v24, v9
	v_lshl_add_u64 v[2:3], v[2:3], 0, v[10:11]
	v_ashrrev_i32_e32 v11, 31, v0
	s_waitcnt lgkmcnt(6)
	v_cvt_pk_bf16_f32 v14, v26, v18
	v_mul_lo_u32 v11, v12, v11
	v_mul_lo_u32 v18, v13, v0
	v_mad_u64_u32 v[40:41], s[22:23], v12, v0, 0
	v_add3_u32 v41, v41, v11, v18
	s_waitcnt lgkmcnt(4)
	v_cvt_pk_bf16_f32 v15, v28, v30
	s_waitcnt lgkmcnt(2)
	v_cvt_pk_bf16_f32 v16, v32, v34
	s_waitcnt lgkmcnt(0)
	v_cvt_pk_bf16_f32 v17, v36, v38
	v_lshl_add_u64 v[40:41], v[40:41], 1, v[2:3]
	v_add_u32_e32 v0, v24, v21
	global_store_dwordx4 v[40:41], v[14:17], off nt
	v_ashrrev_i32_e32 v11, 31, v0
	v_mul_lo_u32 v11, v12, v11
	v_cvt_pk_bf16_f32 v14, v27, v19
	v_cvt_pk_bf16_f32 v15, v29, v31
	v_cvt_pk_bf16_f32 v16, v33, v35
	v_cvt_pk_bf16_f32 v17, v37, v39
	v_mul_lo_u32 v25, v13, v0
	v_mad_u64_u32 v[18:19], s[22:23], v12, v0, 0
	ds_read2_b32 v[26:27], v20 offset0:16 offset1:24
	ds_read2_b32 v[28:29], v20 offset0:49 offset1:57
	ds_read2_b32 v[30:31], v20 offset0:82 offset1:90
	ds_read2_b32 v[32:33], v20 offset0:115 offset1:123
	ds_read2_b32 v[34:35], v20 offset0:148 offset1:156
	ds_read2_b32 v[36:37], v20 offset0:181 offset1:189
	ds_read2_b32 v[38:39], v20 offset0:214 offset1:222
	ds_read2_b32 v[40:41], v20 offset0:247 offset1:255
	v_add3_u32 v19, v19, v11, v25
	v_add_u32_e32 v0, v24, v22
	v_lshl_add_u64 v[18:19], v[18:19], 1, v[2:3]
	v_ashrrev_i32_e32 v11, 31, v0
	global_store_dwordx4 v[18:19], v[14:17], off nt
	v_mul_lo_u32 v11, v12, v11
	v_mul_lo_u32 v25, v13, v0
	v_mad_u64_u32 v[18:19], s[22:23], v12, v0, 0
	v_add3_u32 v19, v19, v11, v25
	v_add_u32_e32 v0, v24, v23
	s_waitcnt lgkmcnt(6)
	v_cvt_pk_bf16_f32 v14, v26, v28
	s_waitcnt lgkmcnt(4)
	v_cvt_pk_bf16_f32 v15, v30, v32
	s_waitcnt lgkmcnt(2)
	v_cvt_pk_bf16_f32 v16, v34, v36
	s_waitcnt lgkmcnt(0)
	v_cvt_pk_bf16_f32 v17, v38, v40
	v_lshl_add_u64 v[18:19], v[18:19], 1, v[2:3]
	v_ashrrev_i32_e32 v11, 31, v0
	global_store_dwordx4 v[18:19], v[14:17], off nt
	v_mul_lo_u32 v11, v12, v11
	v_mul_lo_u32 v18, v13, v0
	v_mad_u64_u32 v[12:13], s[22:23], v12, v0, 0
	v_add3_u32 v13, v13, v11, v18
	v_cvt_pk_bf16_f32 v14, v27, v29
	v_cvt_pk_bf16_f32 v15, v31, v33
	v_cvt_pk_bf16_f32 v16, v35, v37
	v_cvt_pk_bf16_f32 v17, v39, v41
	v_lshl_add_u64 v[2:3], v[12:13], 1, v[2:3]
	global_store_dwordx4 v[2:3], v[14:17], off nt
	v_add_u32_e32 v5, s33, v5
	s_waitcnt lgkmcnt(0)
	v_cmp_lt_i32_e32 vcc, s56, v5
	s_or_b64 s[20:21], vcc, s[20:21]
	s_andn2_b64 exec, exec, s[20:21]
	s_cbranch_execnz .LBB0_1417

.LBB0_1490:
	s_lshl_b32 s13, s12, 1
	s_lshl_b32 s14, s11, 1
	v_or_b32_e32 v9, s13, v1
	v_or_b32_e32 v11, s14, v0
	s_add_i32 s15, s13, 4
	s_add_i32 s16, s14, 4
	s_add_i32 s17, s13, 8
	s_add_i32 s18, s14, 8
	s_add_i32 s19, s13, 12
	s_add_i32 s20, s14, 12
	s_add_i32 s21, s13, 16
	s_add_i32 s22, s14, 16
	s_add_i32 s23, s13, 20
	s_add_i32 s24, s14, 20
	s_add_i32 s25, s13, 24
	s_add_i32 s26, s14, 24
	s_add_i32 s13, s13, 28
	s_add_i32 s14, s14, 28
	v_add_u32_e32 v22, v11, v10
	v_or_b32_e32 v52, s15, v1
	v_or_b32_e32 v53, s16, v0
	v_or_b32_e32 v54, s17, v1
	v_or_b32_e32 v55, s18, v0
	v_or_b32_e32 v56, s19, v1
	v_or_b32_e32 v57, s20, v0
	v_or_b32_e32 v58, s21, v1
	v_or_b32_e32 v59, s22, v0
	v_or_b32_e32 v60, s23, v1
	v_or_b32_e32 v61, s24, v0
	v_or_b32_e32 v62, s25, v1
	v_or_b32_e32 v63, s26, v0
	v_or_b32_e32 v64, s13, v1
	v_or_b32_e32 v65, s14, v0
	v_add_u32_e32 v20, v9, v3
	v_ashrrev_i32_e32 v23, 31, v22
	v_add_u32_e32 v24, v52, v3
	v_add_u32_e32 v26, v53, v10
	v_add_u32_e32 v28, v54, v3
	v_add_u32_e32 v30, v55, v10
	v_add_u32_e32 v32, v56, v3
	v_add_u32_e32 v34, v57, v10
	v_add_u32_e32 v36, v58, v3
	v_add_u32_e32 v38, v59, v10
	v_add_u32_e32 v40, v60, v3
	v_add_u32_e32 v42, v61, v10
	v_add_u32_e32 v44, v62, v3
	v_add_u32_e32 v46, v63, v10
	v_add_u32_e32 v48, v64, v3
	v_add_u32_e32 v50, v65, v10
	v_ashrrev_i32_e32 v21, 31, v20
	v_lshlrev_b64 v[22:23], 13, v[22:23]
	v_ashrrev_i32_e32 v27, 31, v26
	v_ashrrev_i32_e32 v25, 31, v24
	v_ashrrev_i32_e32 v31, 31, v30
	v_ashrrev_i32_e32 v29, 31, v28
	v_ashrrev_i32_e32 v35, 31, v34
	v_ashrrev_i32_e32 v33, 31, v32
	v_ashrrev_i32_e32 v39, 31, v38
	v_ashrrev_i32_e32 v37, 31, v36
	v_ashrrev_i32_e32 v43, 31, v42
	v_ashrrev_i32_e32 v41, 31, v40
	v_ashrrev_i32_e32 v47, 31, v46
	v_ashrrev_i32_e32 v45, 31, v44
	v_ashrrev_i32_e32 v51, 31, v50
	v_ashrrev_i32_e32 v49, 31, v48
	v_lshlrev_b64 v[20:21], 13, v[20:21]
	v_lshl_add_u64 v[22:23], v[12:13], 0, v[22:23]
	v_lshlrev_b64 v[24:25], 13, v[24:25]
	v_lshlrev_b64 v[26:27], 13, v[26:27]
	v_lshlrev_b64 v[28:29], 13, v[28:29]
	v_lshlrev_b64 v[30:31], 13, v[30:31]
	v_lshlrev_b64 v[32:33], 13, v[32:33]
	v_lshlrev_b64 v[34:35], 13, v[34:35]
	v_lshlrev_b64 v[36:37], 13, v[36:37]
	v_lshlrev_b64 v[38:39], 13, v[38:39]
	v_lshlrev_b64 v[40:41], 13, v[40:41]
	v_lshlrev_b64 v[42:43], 13, v[42:43]
	v_lshlrev_b64 v[44:45], 13, v[44:45]
	v_lshlrev_b64 v[46:47], 13, v[46:47]
	v_lshlrev_b64 v[48:49], 13, v[48:49]
	v_lshlrev_b64 v[50:51], 13, v[50:51]
	v_lshl_add_u64 v[20:21], v[12:13], 0, v[20:21]
	v_lshl_add_u64 v[26:27], v[12:13], 0, v[26:27]
	v_lshl_add_u64 v[24:25], v[12:13], 0, v[24:25]
	v_lshl_add_u64 v[30:31], v[12:13], 0, v[30:31]
	v_lshl_add_u64 v[28:29], v[12:13], 0, v[28:29]
	v_lshl_add_u64 v[34:35], v[12:13], 0, v[34:35]
	v_lshl_add_u64 v[32:33], v[12:13], 0, v[32:33]
	v_lshl_add_u64 v[38:39], v[12:13], 0, v[38:39]
	v_lshl_add_u64 v[36:37], v[12:13], 0, v[36:37]
	v_lshl_add_u64 v[42:43], v[12:13], 0, v[42:43]
	v_lshl_add_u64 v[40:41], v[12:13], 0, v[40:41]
	v_lshl_add_u64 v[46:47], v[12:13], 0, v[46:47]
	v_lshl_add_u64 v[44:45], v[12:13], 0, v[44:45]
	v_lshl_add_u64 v[50:51], v[12:13], 0, v[50:51]
	v_lshl_add_u64 v[48:49], v[12:13], 0, v[48:49]
	global_load_dword v66, v[22:23], off nt
	global_load_dword v67, v[20:21], off nt
	global_load_dword v68, v[26:27], off nt
	global_load_dword v69, v[24:25], off nt
	global_load_dword v70, v[30:31], off nt
	global_load_dword v71, v[28:29], off nt
	global_load_dword v72, v[34:35], off nt
	global_load_dword v73, v[32:33], off nt
	global_load_dword v74, v[38:39], off nt
	global_load_dword v75, v[36:37], off nt
	global_load_dword v76, v[42:43], off nt
	global_load_dword v77, v[40:41], off nt
	global_load_dword v78, v[46:47], off nt
	global_load_dword v79, v[44:45], off nt
	global_load_dword v80, v[50:51], off nt
	global_load_dword v81, v[48:49], off nt
	s_add_i32 s11, s11, 16
	s_add_i32 s12, s12, 16
	s_add_i32 s10, s10, -16
	v_mad_u64_u32 v[20:21], s[14:15], v11, s7, v[2:3]
	s_cmp_lg_u32 s10, 0
	v_mad_u64_u32 v[22:23], s[14:15], v9, s7, v[2:3]
	v_mad_u64_u32 v[24:25], s[14:15], v53, s7, v[2:3]
	v_mad_u64_u32 v[26:27], s[14:15], v52, s7, v[2:3]
	v_mad_u64_u32 v[28:29], s[14:15], v55, s7, v[2:3]
	v_mad_u64_u32 v[30:31], s[14:15], v54, s7, v[2:3]
	v_mad_u64_u32 v[32:33], s[14:15], v57, s7, v[2:3]
	v_mad_u64_u32 v[34:35], s[14:15], v56, s7, v[2:3]
	v_mad_u64_u32 v[36:37], s[14:15], v59, s7, v[2:3]
	v_mad_u64_u32 v[38:39], s[14:15], v58, s7, v[2:3]
	v_mad_u64_u32 v[40:41], s[14:15], v61, s7, v[2:3]
	v_mad_u64_u32 v[42:43], s[14:15], v60, s7, v[2:3]
	v_mad_u64_u32 v[44:45], s[14:15], v63, s7, v[2:3]
	v_mad_u64_u32 v[46:47], s[14:15], v62, s7, v[2:3]
	v_mad_u64_u32 v[48:49], s[14:15], v65, s7, v[2:3]
	v_mad_u64_u32 v[50:51], s[14:15], v64, s7, v[2:3]
	s_waitcnt vmcnt(15)
	ds_write_b32 v20, v66
	s_waitcnt vmcnt(14)
	ds_write_b32 v22, v67
	s_waitcnt vmcnt(13)
	ds_write_b32 v24, v68
	s_waitcnt vmcnt(12)
	ds_write_b32 v26, v69
	s_waitcnt vmcnt(11)
	ds_write_b32 v28, v70
	s_waitcnt vmcnt(10)
	ds_write_b32 v30, v71
	s_waitcnt vmcnt(9)
	ds_write_b32 v32, v72
	s_waitcnt vmcnt(8)
	ds_write_b32 v34, v73
	s_waitcnt vmcnt(7)
	ds_write_b32 v36, v74
	s_waitcnt vmcnt(6)
	ds_write_b32 v38, v75
	s_waitcnt vmcnt(5)
	ds_write_b32 v40, v76
	s_waitcnt vmcnt(4)
	ds_write_b32 v42, v77
	s_waitcnt vmcnt(3)
	ds_write_b32 v44, v78
	s_waitcnt vmcnt(2)
	ds_write_b32 v46, v79
	s_waitcnt vmcnt(1)
	ds_write_b32 v48, v80
	s_waitcnt vmcnt(0)
	ds_write_b32 v50, v81
	s_cbranch_scc1 .LBB0_1490
	s_waitcnt lgkmcnt(0)
	ds_read2_b32 v[20:21], v16 offset0:33 offset1:41
	ds_read2_b32 v[22:23], v16 offset1:8
	ds_read2_b32 v[24:25], v16 offset0:66 offset1:74
	ds_read2_b32 v[26:27], v16 offset0:99 offset1:107
	ds_read2_b32 v[28:29], v16 offset0:132 offset1:140
	ds_read2_b32 v[30:31], v16 offset0:165 offset1:173
	ds_read2_b32 v[32:33], v16 offset0:198 offset1:206
	ds_read2_b32 v[34:35], v16 offset0:231 offset1:239
	v_ashrrev_i32_e32 v11, 31, v10
	v_lshl_add_u64 v[36:37], v[10:11], 1, v[6:7]
	v_or_b32_e32 v3, v8, v15
	s_waitcnt lgkmcnt(6)
	v_cvt_pk_bf16_f32 v10, v22, v20
	s_waitcnt lgkmcnt(4)
	v_cvt_pk_bf16_f32 v11, v24, v26
	s_waitcnt lgkmcnt(2)
	v_cvt_pk_bf16_f32 v12, v28, v30
	s_waitcnt lgkmcnt(0)
	v_cvt_pk_bf16_f32 v13, v32, v34
	v_mad_i64_i32 v[38:39], s[10:11], v3, s8, v[36:37]
	global_store_dwordx4 v[38:39], v[10:13], off nt
	v_or_b32_e32 v3, v8, v17
	v_add_u32_e32 v14, s6, v14
	v_cvt_pk_bf16_f32 v10, v23, v21
	v_cvt_pk_bf16_f32 v11, v25, v27
	v_cvt_pk_bf16_f32 v12, v29, v31
	v_cvt_pk_bf16_f32 v13, v33, v35
	ds_read2_b32 v[22:23], v16 offset0:49 offset1:57
	ds_read2_b32 v[24:25], v16 offset0:16 offset1:24
	ds_read2_b32 v[26:27], v16 offset0:82 offset1:90
	ds_read2_b32 v[28:29], v16 offset0:115 offset1:123
	ds_read2_b32 v[30:31], v16 offset0:148 offset1:156
	ds_read2_b32 v[32:33], v16 offset0:181 offset1:189
	ds_read2_b32 v[34:35], v16 offset0:214 offset1:222
	ds_read2_b32 v[38:39], v16 offset0:247 offset1:255
	v_mad_i64_i32 v[20:21], s[10:11], v3, s8, v[36:37]
	v_or_b32_e32 v3, v8, v18
	global_store_dwordx4 v[20:21], v[10:13], off nt
	v_mad_i64_i32 v[20:21], s[10:11], v3, s8, v[36:37]
	s_waitcnt lgkmcnt(6)
	v_cvt_pk_bf16_f32 v10, v24, v22
	s_waitcnt lgkmcnt(4)
	v_cvt_pk_bf16_f32 v11, v26, v28
	s_waitcnt lgkmcnt(2)
	v_cvt_pk_bf16_f32 v12, v30, v32
	s_waitcnt lgkmcnt(0)
	v_cvt_pk_bf16_f32 v13, v34, v38
	v_or_b32_e32 v3, v8, v19
	global_store_dwordx4 v[20:21], v[10:13], off nt
	v_mad_i64_i32 v[8:9], s[10:11], v3, s8, v[36:37]
	s_nop 0
	v_cvt_pk_bf16_f32 v10, v25, v23
	v_cvt_pk_bf16_f32 v11, v27, v29
	v_cvt_pk_bf16_f32 v12, v31, v33
	v_cvt_pk_bf16_f32 v13, v35, v39
	global_store_dwordx4 v[8:9], v[10:13], off nt
	s_waitcnt lgkmcnt(0)
	v_cmp_lt_i32_e32 vcc, s9, v14
	s_or_b64 s[4:5], vcc, s[4:5]
	s_andn2_b64 exec, exec, s[4:5]
	s_cbranch_execnz .LBB0_1489
